# v31 with the compress-GEMM-1 to compress-GEMM-2 hand-off done by write-through (sc1) HID stores instead of an L2 write-back per workgroup
# baseline (speedup 1.0000x reference)
.LBB0_1100:
	v_add_u32_e32 v1, s2, v160
	ds_read2_b32 v[6:7], v1 offset1:1
	s_addk_i32 s2, 0x204
	s_mov_b64 s[4:5], 0x200
	s_cmpk_eq_i32 s2, 0x4080
	s_waitcnt lgkmcnt(0)
	v_pk_add_f32 v[6:7], v[2:3], v[6:7]
	s_nop 0
	v_mul_f32_e32 v1, 0x3d372713, v6
	v_mul_f32_e32 v8, 0x3d372713, v7
	v_mul_f32_e32 v1, v6, v1
	v_mul_f32_e32 v8, v7, v8
	v_fma_f32 v1, v6, v1, v6
	v_fma_f32 v8, v7, v8, v7
	v_mul_f32_e32 v1, 0x3f4c422a, v1
	v_mul_f32_e32 v8, 0x3f4c422a, v8
	v_add_f32_e32 v1, v1, v1
	v_add_f32_e32 v8, v8, v8
	v_mul_f32_e32 v1, 0x3fb8aa3b, v1
	v_mul_f32_e32 v8, 0x3fb8aa3b, v8
	v_exp_f32_e32 v1, v1
	v_exp_f32_e32 v8, v8
	v_pk_mul_f32 v[6:7], v[6:7], 0.5 op_sel_hi:[1,0]
	v_add_f32_e32 v1, 1.0, v1
	v_add_f32_e32 v9, 1.0, v8
	v_rcp_f32_e32 v8, v1
	v_rcp_f32_e32 v9, v9
	s_nop 0
	v_pk_fma_f32 v[8:9], v[8:9], -2.0, 1.0 op_sel_hi:[1,0,0]
	s_nop 0
	v_pk_add_f32 v[8:9], v[8:9], 1.0 op_sel_hi:[1,0]
	s_nop 0
	v_pk_mul_f32 v[6:7], v[6:7], v[8:9]
	s_nop 0
	v_cvt_pk_bf16_f32 v1, v6, v7
	global_store_dword v[4:5], v1, off sc1
	v_lshl_add_u64 v[4:5], v[4:5], 0, s[4:5]
	s_cbranch_scc0 .LBB0_1100
	v_readlane_b32 s2, v255, 3
	s_add_i32 s42, s42, s2
	v_readlane_b32 s2, v255, 6
	v_readlane_b32 s3, v255, 7
	s_add_i32 s43, s43, s94
	s_xor_b64 s[14:15], s[14:15], s[2:3]
	s_cmp_gt_i32 s43, 63
	s_barrier
	s_cbranch_scc0 .LBB0_1061

.Lc2m_start:
	s_waitcnt vmcnt(0)
	s_barrier
	v_cmp_eq_u32_e32 vcc, 0, v208
	s_and_saveexec_b64 s[2:3], vcc
	s_cbranch_execz .Lc2m_sync_done
	s_waitcnt vmcnt(0)
	v_readlane_b32 s4, v254, 4
	v_readlane_b32 s5, v254, 5
	s_lshr_b32 s6, s92, 1
	s_lshl_b32 s6, s6, 2
	s_add_u32 s4, s4, s6
	s_addc_u32 s5, s5, 0
	v_mov_b32_e32 v2, 0
	v_mov_b32_e32 v3, 1
	s_nop 2
	global_atomic_add v2, v3, s[4:5]
	s_bitcmp1_b32 s92, 0
	s_cbranch_scc1 .Lc2m_sync_done
	s_mov_b32 m0, 0
